# B (MLA) loop K/V LDS-DMA issue at MFMA gap 13 (v50 had 9)
# baseline (speedup 1.0000x reference)
; #define SBAR() __builtin_amdgcn_sched_barrier(0)
; #define SGB(mask, n) __builtin_amdgcn_sched_group_barrier(mask, n, 0)
; #define BLOAD(b, k0) do { _Pragma("unroll") for (int i = 0; i < 3; ++i) glds16(Kh + (long)(k0) * 768 + bkoff[i], K_lds + (b) * 24576 + ldst[i]); \
;     _Pragma("unroll") for (int i = 0; i < 2; ++i) glds16(Vh + (long)(k0) * 512 + bvoff[i], V_lds + (b) * 16384 + ldst[i]); } while (0)
; DEV void attn_b_item(const Params& P, int layer, int batch, int item, char* lds) {
;     ...
;     {
;       bf16x8 kf[12];
; #pragma unroll
;       for (int ks = 0; ks < 12; ++ks) kf[ks] = *reinterpret_cast<const bf16x8*>(Ks + kq + (((ks * 2 + hi) ^ ksw) << 4));
; #pragma unroll
;       for (int ks = 0; ks < 12; ++ks) p0 = __builtin_amdgcn_mfma_f32_32x32x16_bf16(kf[ks], qr[ks], p0, 0, 0, 0);
;       SGB(0x100, 4); SGB(0x008, 2); SGB(0x100, 2); SGB(0x008, 2); SGB(0x100, 2); SGB(0x008, 2); SGB(0x100, 2); SGB(0x008, 2); SGB(0x100, 2); SGB(0x008, 4);
;     }
;     SBAR();
;     if (j + 1 < NT) BLOAD((j + 1) & 1, (j + 1) * 64);
;     SBAR();
;     {
;       trq<0, 0>(vb, fa);
;       bf16x8 kf[12];
; #pragma unroll
;       for (int ks = 0; ks < 12; ++ks) kf[ks] = *reinterpret_cast<const bf16x8*>(Ks + kq + 32 * 384 + (((ks * 2 + hi) ^ ksw) << 4));
; #pragma unroll
;       for (int ks = 0; ks < 12; ++ks) p1 = __builtin_amdgcn_mfma_f32_32x32x16_bf16(kf[ks], qr[ks], p1, 0, 0, 0);
;       sm_exp(p0, lsum); sm_pack(p0, pa0, pa1);
;     }
;     asm volatile("s_waitcnt lgkmcnt(0)" ::: "memory"); SBAR();
;     trq<0, 2>(vb, fb);
;     mmaq(o[0], o[1], fa, pa0, pa1);
;     sm_exp(p1, lsum);
;     asm volatile("s_waitcnt lgkmcnt(0)" ::: "memory"); SBAR();
;     trq<2, 0>(vb, fa);
;     mmaq(o[2], o[3], fb, pa0, pa1);
.Lmla_loop:
	ds_read_b128 v[218:221], v169 offset:0
	ds_read_b128 v[232:235], v170 offset:0
	ds_read_b128 v[236:239], v171 offset:0
	ds_read_b128 v[240:243], v172 offset:0
	ds_read_b128 v[244:247], v169 offset:128
	ds_read_b128 v[248:251], v170 offset:128
	v_mfma_f32_32x32x16_bf16 v[48:63], v[198:201], v[202:205], v[48:63]
	ds_read_b128 v[202:205], v171 offset:128
	v_mfma_f32_32x32x16_bf16 v[32:47], v[198:201], v[206:209], v[32:47]
	ds_read_b128 v[206:209], v172 offset:128
	v_mfma_f32_32x32x16_bf16 v[16:31], v[198:201], v[210:213], v[16:31]
	ds_read_b128 v[210:213], v169 offset:256
	v_mfma_f32_32x32x16_bf16 v[0:15], v[198:201], v[214:217], v[0:15]
	ds_read_b128 v[214:217], v170 offset:256
	s_waitcnt lgkmcnt(9)
	v_mfma_f32_32x32x16_bf16 v[64:79], v[218:221], v[96:99], 0
	ds_read_b128 v[218:221], v171 offset:256
	v_add_f32_e32 v182, v182, v80
	v_add_f32_e32 v182, v182, v81
	s_waitcnt lgkmcnt(9)
	v_mfma_f32_32x32x16_bf16 v[64:79], v[232:235], v[100:103], v[64:79]
	ds_read_b128 v[232:235], v172 offset:256
	v_add_f32_e32 v182, v182, v82
	s_waitcnt lgkmcnt(9)
	v_mfma_f32_32x32x16_bf16 v[64:79], v[236:239], v[104:107], v[64:79]
	ds_read_b128 v[236:239], v169 offset:12288
	v_add_f32_e32 v182, v182, v83
	s_waitcnt lgkmcnt(9)
	v_mfma_f32_32x32x16_bf16 v[64:79], v[240:243], v[108:111], v[64:79]
	ds_read_b128 v[240:243], v170 offset:12288
	v_add_f32_e32 v182, v182, v84
	v_add_f32_e32 v182, v182, v85
	s_waitcnt lgkmcnt(9)
	v_mfma_f32_32x32x16_bf16 v[64:79], v[244:247], v[112:115], v[64:79]
	ds_read_b128 v[244:247], v171 offset:12288
	v_add_f32_e32 v182, v182, v86
	s_waitcnt lgkmcnt(9)
	v_mfma_f32_32x32x16_bf16 v[64:79], v[248:251], v[116:119], v[64:79]
	ds_read_b128 v[248:251], v172 offset:12288
	v_add_f32_e32 v182, v182, v87
	s_waitcnt lgkmcnt(9)
	v_mfma_f32_32x32x16_bf16 v[64:79], v[202:205], v[120:123], v[64:79]
	ds_read_b128 v[202:205], v169 offset:12416
	v_add_f32_e32 v182, v182, v88
	v_add_f32_e32 v182, v182, v89
	s_waitcnt lgkmcnt(9)
	v_mfma_f32_32x32x16_bf16 v[64:79], v[206:209], v[124:127], v[64:79]
	ds_read_b128 v[206:209], v170 offset:12416
	v_add_f32_e32 v182, v182, v90
	s_waitcnt lgkmcnt(9)
	v_mfma_f32_32x32x16_bf16 v[64:79], v[210:213], v[128:131], v[64:79]
	ds_read_b128 v[210:213], v171 offset:12416
	v_add_f32_e32 v182, v182, v91
	s_waitcnt lgkmcnt(9)
	v_mfma_f32_32x32x16_bf16 v[64:79], v[214:217], v[132:135], v[64:79]
	ds_read_b128 v[214:217], v172 offset:12416
	v_add_f32_e32 v182, v182, v92
	v_add_f32_e32 v182, v182, v93
	s_add_u32 m0, s100, 0x6000
	s_nop 0
	global_load_lds_dwordx4 v146, s[68:69]
	s_add_u32 m0, s101, 0x4000
	s_nop 0
	global_load_lds_dwordx4 v148, s[70:71]
	s_add_u32 m0, s100, 0x8000
	s_nop 0
	global_load_lds_dwordx4 v150, s[68:69]
	s_add_u32 m0, s101, 0x6000
	s_nop 0
	global_load_lds_dwordx4 v152, s[70:71]
	s_add_u32 m0, s100, 0xa000
	s_nop 0
	global_load_lds_dwordx4 v154, s[68:69]
	s_add_u32 s68, s68, 0x18000
	s_addc_u32 s69, s69, 0
	s_add_u32 s70, s70, 0x10000
	s_addc_u32 s71, s71, 0
	s_waitcnt lgkmcnt(9)
	v_mfma_f32_32x32x16_bf16 v[64:79], v[218:221], v[136:139], v[64:79]
	ds_read_b128 v[218:221], v169 offset:12544
	v_add_f32_e32 v182, v182, v94
	s_waitcnt lgkmcnt(9)
	v_mfma_f32_32x32x16_bf16 v[64:79], v[232:235], v[140:143], v[64:79]
	ds_read_b128 v[232:235], v170 offset:12544
	v_add_f32_e32 v182, v182, v95
	s_waitcnt lgkmcnt(9)
	v_mfma_f32_32x32x16_bf16 v[80:95], v[236:239], v[96:99], 0
	ds_read_b128 v[236:239], v171 offset:12544
	s_waitcnt lgkmcnt(9)
	v_mfma_f32_32x32x16_bf16 v[80:95], v[240:243], v[100:103], v[80:95]
	ds_read_b128 v[240:243], v172 offset:12544
	s_waitcnt lgkmcnt(9)
	v_mfma_f32_32x32x16_bf16 v[80:95], v[244:247], v[104:107], v[80:95]
	ds_read_b64_tr_b16 v[244:245], v166 offset:0
	ds_read_b64_tr_b16 v[246:247], v166 offset:2048
	s_waitcnt lgkmcnt(10)
	v_mfma_f32_32x32x16_bf16 v[80:95], v[248:251], v[108:111], v[80:95]
	ds_read_b64_tr_b16 v[248:249], v166 offset:512
	ds_read_b64_tr_b16 v[250:251], v166 offset:2560
	v_exp_f32_e32 v64, v64
	v_exp_f32_e32 v65, v65
	s_waitcnt lgkmcnt(11)
	v_mfma_f32_32x32x16_bf16 v[80:95], v[202:205], v[112:115], v[80:95]
	ds_read_b64_tr_b16 v[202:203], v166 offset:1024
	ds_read_b64_tr_b16 v[204:205], v166 offset:3072
	v_exp_f32_e32 v66, v66
	v_exp_f32_e32 v67, v67
	s_waitcnt lgkmcnt(12)
	v_mfma_f32_32x32x16_bf16 v[80:95], v[206:209], v[116:119], v[80:95]
	ds_read_b64_tr_b16 v[206:207], v166 offset:1536
	ds_read_b64_tr_b16 v[208:209], v166 offset:3584
	v_exp_f32_e32 v68, v68
	v_exp_f32_e32 v69, v69
	s_waitcnt lgkmcnt(13)
	v_mfma_f32_32x32x16_bf16 v[80:95], v[210:213], v[120:123], v[80:95]
	ds_read_b64_tr_b16 v[210:211], v166 offset:4096
	ds_read_b64_tr_b16 v[212:213], v166 offset:6144
	v_exp_f32_e32 v70, v70
	v_exp_f32_e32 v71, v71
	s_waitcnt lgkmcnt(14)
	v_mfma_f32_32x32x16_bf16 v[80:95], v[214:217], v[124:127], v[80:95]
	ds_read_b64_tr_b16 v[214:215], v166 offset:4608
	ds_read_b64_tr_b16 v[216:217], v166 offset:6656
	v_cvt_pk_bf16_f32 v174, v64, v65
	v_exp_f32_e32 v72, v72
	v_exp_f32_e32 v73, v73
	s_waitcnt lgkmcnt(14)
	v_mfma_f32_32x32x16_bf16 v[80:95], v[218:221], v[128:131], v[80:95]
	ds_read_b64_tr_b16 v[218:219], v166 offset:5120
	ds_read_b64_tr_b16 v[220:221], v166 offset:7168
	v_cvt_pk_bf16_f32 v175, v66, v67
	v_exp_f32_e32 v74, v74
	v_exp_f32_e32 v75, v75
	s_waitcnt lgkmcnt(14)
	v_mfma_f32_32x32x16_bf16 v[80:95], v[232:235], v[132:135], v[80:95]
	ds_read_b64_tr_b16 v[232:233], v166 offset:5632
	ds_read_b64_tr_b16 v[234:235], v166 offset:7680
	v_cvt_pk_bf16_f32 v176, v68, v69
	v_exp_f32_e32 v76, v76
	v_exp_f32_e32 v77, v77
	s_waitcnt lgkmcnt(14)
; #define SBAR() __builtin_amdgcn_sched_barrier(0)
; #define SGB(mask, n) __builtin_amdgcn_sched_group_barrier(mask, n, 0)
; #define BLOAD(b, k0) do { _Pragma("unroll") for (int i = 0; i < 3; ++i) glds16(Kh + (long)(k0) * 768 + bkoff[i], K_lds + (b) * 24576 + ldst[i]); \
;     _Pragma("unroll") for (int i = 0; i < 2; ++i) glds16(Vh + (long)(k0) * 512 + bvoff[i], V_lds + (b) * 16384 + ldst[i]); } while (0)
; DEV void attn_b_item(const Params& P, int layer, int batch, int item, char* lds) {
;     ...
;     {
;       bf16x8 kf[12];
; #pragma unroll
;       for (int ks = 0; ks < 12; ++ks) kf[ks] = *reinterpret_cast<const bf16x8*>(Ks + kq + (((ks * 2 + hi) ^ ksw) << 4));
; #pragma unroll
;       for (int ks = 0; ks < 12; ++ks) p0 = __builtin_amdgcn_mfma_f32_32x32x16_bf16(kf[ks], qr[ks], p0, 0, 0, 0);
;       SGB(0x100, 4); SGB(0x008, 2); SGB(0x100, 2); SGB(0x008, 2); SGB(0x100, 2); SGB(0x008, 2); SGB(0x100, 2); SGB(0x008, 2); SGB(0x100, 2); SGB(0x008, 4);
;     }
;     SBAR();
;     if (j + 1 < NT) BLOAD((j + 1) & 1, (j + 1) * 64);
;     SBAR();
;     {
;       trq<0, 0>(vb, fa);
;       bf16x8 kf[12];
; #pragma unroll
;       for (int ks = 0; ks < 12; ++ks) kf[ks] = *reinterpret_cast<const bf16x8*>(Ks + kq + 32 * 384 + (((ks * 2 + hi) ^ ksw) << 4));
; #pragma unroll
;       for (int ks = 0; ks < 12; ++ks) p1 = __builtin_amdgcn_mfma_f32_32x32x16_bf16(kf[ks], qr[ks], p1, 0, 0, 0);
;       sm_exp(p0, lsum); sm_pack(p0, pa0, pa1);
;     }
;     asm volatile("s_waitcnt lgkmcnt(0)" ::: "memory"); SBAR();
;     trq<0, 2>(vb, fb);
;     mmaq(o[0], o[1], fa, pa0, pa1);
;     sm_exp(p1, lsum);
;     asm volatile("s_waitcnt lgkmcnt(0)" ::: "memory"); SBAR();
;     trq<2, 0>(vb, fa);
;     mmaq(o[2], o[3], fb, pa0, pa1);
;     sm_pack(p1, pa2, pa3);
;     asm volatile("s_waitcnt lgkmcnt(0)" ::: "memory"); SBAR();
;     trq<2, 2>(vb, fb);
;     mmaq(o[0], o[1], fa, pa2, pa3);
;     asm volatile("s_waitcnt lgkmcnt(0)" ::: "memory"); SBAR();
;     mmaq(o[2], o[3], fb, pa2, pa3);
;     asm volatile("s_waitcnt vmcnt(0)" ::: "memory");
;     __syncthreads();
	v_mfma_f32_32x32x16_bf16 v[80:95], v[236:239], v[136:139], v[80:95]
	ds_read_b64_tr_b16 v[236:237], v166 offset:8192
	ds_read_b64_tr_b16 v[238:239], v166 offset:10240
	v_cvt_pk_bf16_f32 v177, v70, v71
	v_exp_f32_e32 v78, v78
	v_exp_f32_e32 v79, v79
	s_waitcnt lgkmcnt(14)
	v_mfma_f32_32x32x16_bf16 v[80:95], v[240:243], v[140:143], v[80:95]
	ds_read_b64_tr_b16 v[240:241], v166 offset:8704
	ds_read_b64_tr_b16 v[242:243], v166 offset:10752
	v_cvt_pk_bf16_f32 v178, v72, v73
	v_cvt_pk_bf16_f32 v179, v74, v75
	v_cvt_pk_bf16_f32 v180, v76, v77
	v_cvt_pk_bf16_f32 v181, v78, v79
	s_waitcnt lgkmcnt(14)
	v_mfma_f32_32x32x16_bf16 v[48:63], v[174:177], v[244:247], v[48:63]
	ds_read_b64_tr_b16 v[244:245], v166 offset:9216
	ds_read_b64_tr_b16 v[246:247], v166 offset:11264
	v_add_f32_e32 v182, v182, v64
	v_add_f32_e32 v182, v182, v65
	v_add_f32_e32 v182, v182, v66
	v_add_f32_e32 v182, v182, v67
	s_waitcnt lgkmcnt(14)
	v_mfma_f32_32x32x16_bf16 v[32:47], v[174:177], v[248:251], v[32:47]
	ds_read_b64_tr_b16 v[248:249], v166 offset:9728
	ds_read_b64_tr_b16 v[250:251], v166 offset:11776
	v_add_f32_e32 v182, v182, v68
	v_add_f32_e32 v182, v182, v69
	v_add_f32_e32 v182, v182, v70
	v_add_f32_e32 v182, v182, v71
	s_waitcnt lgkmcnt(14)
	v_mfma_f32_32x32x16_bf16 v[16:31], v[174:177], v[202:205], v[16:31]
	ds_read_b64_tr_b16 v[202:203], v166 offset:12288
	ds_read_b64_tr_b16 v[204:205], v166 offset:14336
	v_add_f32_e32 v182, v182, v72
	v_add_f32_e32 v182, v182, v73
	v_add_f32_e32 v182, v182, v74
	v_add_f32_e32 v182, v182, v75
	s_waitcnt lgkmcnt(14)
	v_mfma_f32_32x32x16_bf16 v[0:15], v[174:177], v[206:209], v[0:15]
	ds_read_b64_tr_b16 v[206:207], v166 offset:12800
	ds_read_b64_tr_b16 v[208:209], v166 offset:14848
	v_exp_f32_e32 v80, v80
	v_exp_f32_e32 v81, v81
	v_exp_f32_e32 v82, v82
	s_waitcnt lgkmcnt(14)
	v_mfma_f32_32x32x16_bf16 v[48:63], v[178:181], v[210:213], v[48:63]
	ds_read_b64_tr_b16 v[210:211], v166 offset:13312
	ds_read_b64_tr_b16 v[212:213], v166 offset:15360
	v_exp_f32_e32 v83, v83
	v_exp_f32_e32 v84, v84
	v_exp_f32_e32 v85, v85
	s_waitcnt lgkmcnt(14)
	v_mfma_f32_32x32x16_bf16 v[32:47], v[178:181], v[214:217], v[32:47]
	ds_read_b64_tr_b16 v[214:215], v166 offset:13824
	ds_read_b64_tr_b16 v[216:217], v166 offset:15872
	v_exp_f32_e32 v86, v86
	v_exp_f32_e32 v87, v87
	v_exp_f32_e32 v88, v88
	s_waitcnt lgkmcnt(14)
	v_mfma_f32_32x32x16_bf16 v[16:31], v[178:181], v[218:221], v[16:31]
	v_cvt_pk_bf16_f32 v194, v80, v81
	v_cvt_pk_bf16_f32 v195, v82, v83
	v_exp_f32_e32 v89, v89
	v_exp_f32_e32 v90, v90
	v_exp_f32_e32 v91, v91
	s_waitcnt lgkmcnt(14)
	v_mfma_f32_32x32x16_bf16 v[0:15], v[178:181], v[232:235], v[0:15]
	v_cvt_pk_bf16_f32 v196, v84, v85
	v_cvt_pk_bf16_f32 v197, v86, v87
	v_exp_f32_e32 v92, v92
	v_exp_f32_e32 v93, v93
	s_waitcnt lgkmcnt(14)
	v_mfma_f32_32x32x16_bf16 v[48:63], v[194:197], v[236:239], v[48:63]
	v_exp_f32_e32 v94, v94
	v_exp_f32_e32 v95, v95
	s_waitcnt lgkmcnt(12)
	v_mfma_f32_32x32x16_bf16 v[32:47], v[194:197], v[240:243], v[32:47]
	v_cvt_pk_bf16_f32 v198, v88, v89
	v_cvt_pk_bf16_f32 v199, v90, v91
	v_add_f32_e32 v182, v182, v76
	v_add_f32_e32 v182, v182, v77
	s_waitcnt lgkmcnt(10)
	v_mfma_f32_32x32x16_bf16 v[16:31], v[194:197], v[244:247], v[16:31]
	v_cvt_pk_bf16_f32 v200, v92, v93
	v_cvt_pk_bf16_f32 v201, v94, v95
	v_add_f32_e32 v182, v182, v78
	v_add_f32_e32 v182, v182, v79
	s_waitcnt lgkmcnt(8)
	v_mfma_f32_32x32x16_bf16 v[0:15], v[194:197], v[248:251], v[0:15]
	s_waitcnt lgkmcnt(0)
	s_waitcnt vmcnt(0)
	s_barrier
	ds_read_b128 v[218:221], v169 offset:24576
	ds_read_b128 v[232:235], v170 offset:24576
	ds_read_b128 v[236:239], v171 offset:24576
	ds_read_b128 v[240:243], v172 offset:24576
	ds_read_b128 v[244:247], v169 offset:24704
	ds_read_b128 v[248:251], v170 offset:24704
	v_mfma_f32_32x32x16_bf16 v[48:63], v[198:201], v[202:205], v[48:63]
	ds_read_b128 v[202:205], v171 offset:24704
	v_mfma_f32_32x32x16_bf16 v[32:47], v[198:201], v[206:209], v[32:47]
	ds_read_b128 v[206:209], v172 offset:24704
	v_mfma_f32_32x32x16_bf16 v[16:31], v[198:201], v[210:213], v[16:31]
	ds_read_b128 v[210:213], v169 offset:24832
	v_mfma_f32_32x32x16_bf16 v[0:15], v[198:201], v[214:217], v[0:15]
	ds_read_b128 v[214:217], v170 offset:24832
	s_waitcnt lgkmcnt(9)
	v_mfma_f32_32x32x16_bf16 v[64:79], v[218:221], v[96:99], 0
	ds_read_b128 v[218:221], v171 offset:24832
	v_add_f32_e32 v182, v182, v80
	v_add_f32_e32 v182, v182, v81
	s_waitcnt lgkmcnt(9)
	v_mfma_f32_32x32x16_bf16 v[64:79], v[232:235], v[100:103], v[64:79]
	ds_read_b128 v[232:235], v172 offset:24832
	v_add_f32_e32 v182, v182, v82
	s_waitcnt lgkmcnt(9)
	v_mfma_f32_32x32x16_bf16 v[64:79], v[236:239], v[104:107], v[64:79]
	ds_read_b128 v[236:239], v169 offset:36864
	v_add_f32_e32 v182, v182, v83
	s_waitcnt lgkmcnt(9)
	v_mfma_f32_32x32x16_bf16 v[64:79], v[240:243], v[108:111], v[64:79]
	ds_read_b128 v[240:243], v170 offset:36864
	v_add_f32_e32 v182, v182, v84
	v_add_f32_e32 v182, v182, v85
	s_waitcnt lgkmcnt(9)
	v_mfma_f32_32x32x16_bf16 v[64:79], v[244:247], v[112:115], v[64:79]
	ds_read_b128 v[244:247], v171 offset:36864
	v_add_f32_e32 v182, v182, v86
	s_waitcnt lgkmcnt(9)
	v_mfma_f32_32x32x16_bf16 v[64:79], v[248:251], v[116:119], v[64:79]
	ds_read_b128 v[248:251], v172 offset:36864
	v_add_f32_e32 v182, v182, v87
	s_waitcnt lgkmcnt(9)
	v_mfma_f32_32x32x16_bf16 v[64:79], v[202:205], v[120:123], v[64:79]
	ds_read_b128 v[202:205], v169 offset:36992
	v_add_f32_e32 v182, v182, v88
	v_add_f32_e32 v182, v182, v89
	s_waitcnt lgkmcnt(9)
	v_mfma_f32_32x32x16_bf16 v[64:79], v[206:209], v[124:127], v[64:79]
	ds_read_b128 v[206:209], v170 offset:36992
	v_add_f32_e32 v182, v182, v90
	s_waitcnt lgkmcnt(9)
	v_mfma_f32_32x32x16_bf16 v[64:79], v[210:213], v[128:131], v[64:79]
	ds_read_b128 v[210:213], v171 offset:36992
	v_add_f32_e32 v182, v182, v91
	s_waitcnt lgkmcnt(9)
	v_mfma_f32_32x32x16_bf16 v[64:79], v[214:217], v[132:135], v[64:79]
	ds_read_b128 v[214:217], v172 offset:36992
	v_add_f32_e32 v182, v182, v92
	v_add_f32_e32 v182, v182, v93
	s_add_u32 s22, s65, 2
	s_cmp_ge_u32 s22, s50
	s_cbranch_scc1 .Lmla_skipdma_o
	s_add_u32 m0, s100, 0x0
	s_nop 0
	global_load_lds_dwordx4 v146, s[68:69]
	s_add_u32 m0, s101, 0x0
	s_nop 0
	global_load_lds_dwordx4 v148, s[70:71]
	s_add_u32 m0, s100, 0x2000
	s_nop 0
	global_load_lds_dwordx4 v150, s[68:69]
	s_add_u32 m0, s101, 0x2000
	s_nop 0
	global_load_lds_dwordx4 v152, s[70:71]
	s_add_u32 m0, s100, 0x4000
	s_nop 0
	global_load_lds_dwordx4 v154, s[68:69]
	s_add_u32 s68, s68, 0x18000
	s_addc_u32 s69, s69, 0
	s_add_u32 s70, s70, 0x10000
	s_addc_u32 s71, s71, 0
; #define SBAR() __builtin_amdgcn_sched_barrier(0)
; #define SGB(mask, n) __builtin_amdgcn_sched_group_barrier(mask, n, 0)
; #define BLOAD(b, k0) do { _Pragma("unroll") for (int i = 0; i < 3; ++i) glds16(Kh + (long)(k0) * 768 + bkoff[i], K_lds + (b) * 24576 + ldst[i]); \
;     _Pragma("unroll") for (int i = 0; i < 2; ++i) glds16(Vh + (long)(k0) * 512 + bvoff[i], V_lds + (b) * 16384 + ldst[i]); } while (0)
; DEV void attn_b_item(const Params& P, int layer, int batch, int item, char* lds) {
;     ...
;       for (int ks = 0; ks < 12; ++ks) kf[ks] = *reinterpret_cast<const bf16x8*>(Ks + kq + (((ks * 2 + hi) ^ ksw) << 4));
; #pragma unroll
;       for (int ks = 0; ks < 12; ++ks) p0 = __builtin_amdgcn_mfma_f32_32x32x16_bf16(kf[ks], qr[ks], p0, 0, 0, 0);
;       SGB(0x100, 4); SGB(0x008, 2); SGB(0x100, 2); SGB(0x008, 2); SGB(0x100, 2); SGB(0x008, 2); SGB(0x100, 2); SGB(0x008, 2); SGB(0x100, 2); SGB(0x008, 4);
;     }
;     SBAR();
;     if (j + 1 < NT) BLOAD((j + 1) & 1, (j + 1) * 64);
;     SBAR();
;     {
;       trq<0, 0>(vb, fa);
;       bf16x8 kf[12];
; #pragma unroll
;       for (int ks = 0; ks < 12; ++ks) kf[ks] = *reinterpret_cast<const bf16x8*>(Ks + kq + 32 * 384 + (((ks * 2 + hi) ^ ksw) << 4));
; #pragma unroll
;       for (int ks = 0; ks < 12; ++ks) p1 = __builtin_amdgcn_mfma_f32_32x32x16_bf16(kf[ks], qr[ks], p1, 0, 0, 0);
;       sm_exp(p0, lsum); sm_pack(p0, pa0, pa1);
;     }
;     asm volatile("s_waitcnt lgkmcnt(0)" ::: "memory"); SBAR();
;     trq<0, 2>(vb, fb);
;     mmaq(o[0], o[1], fa, pa0, pa1);
;     sm_exp(p1, lsum);
;     asm volatile("s_waitcnt lgkmcnt(0)" ::: "memory"); SBAR();
;     trq<2, 0>(vb, fa);
;     mmaq(o[2], o[3], fb, pa0, pa1);
;     sm_pack(p1, pa2, pa3);
;     asm volatile("s_waitcnt lgkmcnt(0)" ::: "memory"); SBAR();
;     trq<2, 2>(vb, fb);
;     mmaq(o[0], o[1], fa, pa2, pa3);
;     asm volatile("s_waitcnt lgkmcnt(0)" ::: "memory"); SBAR();
;     mmaq(o[2], o[3], fb, pa2, pa3);
;     asm volatile("s_waitcnt vmcnt(0)" ::: "memory");
;     __syncthreads();
.Lmla_skipdma_o:
	s_waitcnt lgkmcnt(9)
	v_mfma_f32_32x32x16_bf16 v[64:79], v[218:221], v[136:139], v[64:79]
	ds_read_b128 v[218:221], v169 offset:37120
	v_add_f32_e32 v182, v182, v94
	s_waitcnt lgkmcnt(9)
	v_mfma_f32_32x32x16_bf16 v[64:79], v[232:235], v[140:143], v[64:79]
	ds_read_b128 v[232:235], v170 offset:37120
	v_add_f32_e32 v182, v182, v95
	s_waitcnt lgkmcnt(9)
	v_mfma_f32_32x32x16_bf16 v[80:95], v[236:239], v[96:99], 0
	ds_read_b128 v[236:239], v171 offset:37120
	s_waitcnt lgkmcnt(9)
	v_mfma_f32_32x32x16_bf16 v[80:95], v[240:243], v[100:103], v[80:95]
	ds_read_b128 v[240:243], v172 offset:37120
	s_waitcnt lgkmcnt(9)
	v_mfma_f32_32x32x16_bf16 v[80:95], v[244:247], v[104:107], v[80:95]
	ds_read_b64_tr_b16 v[244:245], v166 offset:16384
	ds_read_b64_tr_b16 v[246:247], v166 offset:18432
	s_waitcnt lgkmcnt(10)
	v_mfma_f32_32x32x16_bf16 v[80:95], v[248:251], v[108:111], v[80:95]
	ds_read_b64_tr_b16 v[248:249], v166 offset:16896
	ds_read_b64_tr_b16 v[250:251], v166 offset:18944
	v_exp_f32_e32 v64, v64
	v_exp_f32_e32 v65, v65
	s_waitcnt lgkmcnt(11)
	v_mfma_f32_32x32x16_bf16 v[80:95], v[202:205], v[112:115], v[80:95]
	ds_read_b64_tr_b16 v[202:203], v166 offset:17408
	ds_read_b64_tr_b16 v[204:205], v166 offset:19456
	v_exp_f32_e32 v66, v66
	v_exp_f32_e32 v67, v67
	s_waitcnt lgkmcnt(12)
	v_mfma_f32_32x32x16_bf16 v[80:95], v[206:209], v[116:119], v[80:95]
	ds_read_b64_tr_b16 v[206:207], v166 offset:17920
	ds_read_b64_tr_b16 v[208:209], v166 offset:19968
	v_exp_f32_e32 v68, v68
	v_exp_f32_e32 v69, v69
	s_waitcnt lgkmcnt(13)
	v_mfma_f32_32x32x16_bf16 v[80:95], v[210:213], v[120:123], v[80:95]
	ds_read_b64_tr_b16 v[210:211], v166 offset:20480
	ds_read_b64_tr_b16 v[212:213], v166 offset:22528
	v_exp_f32_e32 v70, v70
	v_exp_f32_e32 v71, v71
	s_waitcnt lgkmcnt(14)
	v_mfma_f32_32x32x16_bf16 v[80:95], v[214:217], v[124:127], v[80:95]
	ds_read_b64_tr_b16 v[214:215], v166 offset:20992
	ds_read_b64_tr_b16 v[216:217], v166 offset:23040
	v_cvt_pk_bf16_f32 v174, v64, v65
	v_exp_f32_e32 v72, v72
	v_exp_f32_e32 v73, v73
	s_waitcnt lgkmcnt(14)
	v_mfma_f32_32x32x16_bf16 v[80:95], v[218:221], v[128:131], v[80:95]
	ds_read_b64_tr_b16 v[218:219], v166 offset:21504
	ds_read_b64_tr_b16 v[220:221], v166 offset:23552
	v_cvt_pk_bf16_f32 v175, v66, v67
	v_exp_f32_e32 v74, v74
	v_exp_f32_e32 v75, v75
	s_waitcnt lgkmcnt(14)
	v_mfma_f32_32x32x16_bf16 v[80:95], v[232:235], v[132:135], v[80:95]
	ds_read_b64_tr_b16 v[232:233], v166 offset:22016
	ds_read_b64_tr_b16 v[234:235], v166 offset:24064
	v_cvt_pk_bf16_f32 v176, v68, v69
	v_exp_f32_e32 v76, v76
	v_exp_f32_e32 v77, v77
	s_waitcnt lgkmcnt(14)
	v_mfma_f32_32x32x16_bf16 v[80:95], v[236:239], v[136:139], v[80:95]
	ds_read_b64_tr_b16 v[236:237], v166 offset:24576
	ds_read_b64_tr_b16 v[238:239], v166 offset:26624
	v_cvt_pk_bf16_f32 v177, v70, v71
	v_exp_f32_e32 v78, v78
	v_exp_f32_e32 v79, v79
	s_waitcnt lgkmcnt(14)
	v_mfma_f32_32x32x16_bf16 v[80:95], v[240:243], v[140:143], v[80:95]
	ds_read_b64_tr_b16 v[240:241], v166 offset:25088
	ds_read_b64_tr_b16 v[242:243], v166 offset:27136
	v_cvt_pk_bf16_f32 v178, v72, v73
	v_cvt_pk_bf16_f32 v179, v74, v75
	v_cvt_pk_bf16_f32 v180, v76, v77
	v_cvt_pk_bf16_f32 v181, v78, v79
	s_waitcnt lgkmcnt(14)
	v_mfma_f32_32x32x16_bf16 v[48:63], v[174:177], v[244:247], v[48:63]
	ds_read_b64_tr_b16 v[244:245], v166 offset:25600
	ds_read_b64_tr_b16 v[246:247], v166 offset:27648
	v_add_f32_e32 v182, v182, v64
	v_add_f32_e32 v182, v182, v65
	v_add_f32_e32 v182, v182, v66
	v_add_f32_e32 v182, v182, v67
	s_waitcnt lgkmcnt(14)
	v_mfma_f32_32x32x16_bf16 v[32:47], v[174:177], v[248:251], v[32:47]
	ds_read_b64_tr_b16 v[248:249], v166 offset:26112
	ds_read_b64_tr_b16 v[250:251], v166 offset:28160
	v_add_f32_e32 v182, v182, v68
	v_add_f32_e32 v182, v182, v69
	v_add_f32_e32 v182, v182, v70
	v_add_f32_e32 v182, v182, v71
	s_waitcnt lgkmcnt(14)
	v_mfma_f32_32x32x16_bf16 v[16:31], v[174:177], v[202:205], v[16:31]
	ds_read_b64_tr_b16 v[202:203], v166 offset:28672
	ds_read_b64_tr_b16 v[204:205], v166 offset:30720
	v_add_f32_e32 v182, v182, v72
	v_add_f32_e32 v182, v182, v73
	v_add_f32_e32 v182, v182, v74
	v_add_f32_e32 v182, v182, v75
	s_waitcnt lgkmcnt(14)
	v_mfma_f32_32x32x16_bf16 v[0:15], v[174:177], v[206:209], v[0:15]
	ds_read_b64_tr_b16 v[206:207], v166 offset:29184
	ds_read_b64_tr_b16 v[208:209], v166 offset:31232
	v_exp_f32_e32 v80, v80
	v_exp_f32_e32 v81, v81
	v_exp_f32_e32 v82, v82
	s_waitcnt lgkmcnt(14)
	v_mfma_f32_32x32x16_bf16 v[48:63], v[178:181], v[210:213], v[48:63]
	ds_read_b64_tr_b16 v[210:211], v166 offset:29696
	ds_read_b64_tr_b16 v[212:213], v166 offset:31744
	v_exp_f32_e32 v83, v83
	v_exp_f32_e32 v84, v84
	v_exp_f32_e32 v85, v85
	s_waitcnt lgkmcnt(14)
	v_mfma_f32_32x32x16_bf16 v[32:47], v[178:181], v[214:217], v[32:47]
	ds_read_b64_tr_b16 v[214:215], v166 offset:30208
	ds_read_b64_tr_b16 v[216:217], v166 offset:32256
	v_exp_f32_e32 v86, v86
	v_exp_f32_e32 v87, v87
	v_exp_f32_e32 v88, v88
	s_waitcnt lgkmcnt(14)
	v_mfma_f32_32x32x16_bf16 v[16:31], v[178:181], v[218:221], v[16:31]
	v_cvt_pk_bf16_f32 v194, v80, v81
	v_cvt_pk_bf16_f32 v195, v82, v83
	v_exp_f32_e32 v89, v89
	v_exp_f32_e32 v90, v90
	v_exp_f32_e32 v91, v91
	s_waitcnt lgkmcnt(14)
	v_mfma_f32_32x32x16_bf16 v[0:15], v[178:181], v[232:235], v[0:15]
	v_cvt_pk_bf16_f32 v196, v84, v85
	v_cvt_pk_bf16_f32 v197, v86, v87
	v_exp_f32_e32 v92, v92
	v_exp_f32_e32 v93, v93
	s_waitcnt lgkmcnt(14)
	v_mfma_f32_32x32x16_bf16 v[48:63], v[194:197], v[236:239], v[48:63]
	v_exp_f32_e32 v94, v94
	v_exp_f32_e32 v95, v95
	s_waitcnt lgkmcnt(12)
	v_mfma_f32_32x32x16_bf16 v[32:47], v[194:197], v[240:243], v[32:47]
	v_cvt_pk_bf16_f32 v198, v88, v89
	v_cvt_pk_bf16_f32 v199, v90, v91
	v_add_f32_e32 v182, v182, v76
	v_add_f32_e32 v182, v182, v77
	s_waitcnt lgkmcnt(10)
	v_mfma_f32_32x32x16_bf16 v[16:31], v[194:197], v[244:247], v[16:31]
	v_cvt_pk_bf16_f32 v200, v92, v93
	v_cvt_pk_bf16_f32 v201, v94, v95
	v_add_f32_e32 v182, v182, v78
	v_add_f32_e32 v182, v182, v79
	s_waitcnt lgkmcnt(8)
	v_mfma_f32_32x32x16_bf16 v[0:15], v[194:197], v[248:251], v[0:15]
	s_waitcnt lgkmcnt(0)
	s_waitcnt vmcnt(0)
	s_barrier
	s_add_u32 s65, s65, 2
	s_cmp_lt_u32 s65, s50
	s_cbranch_scc1 .Lmla_loop
	v_mfma_f32_32x32x16_bf16 v[48:63], v[198:201], v[202:205], v[48:63]
	v_add_f32_e32 v182, v182, v80
	v_add_f32_e32 v182, v182, v81
	v_add_f32_e32 v182, v182, v82
	v_add_f32_e32 v182, v182, v83
	v_mfma_f32_32x32x16_bf16 v[32:47], v[198:201], v[206:209], v[32:47]
	v_add_f32_e32 v182, v182, v84
	v_add_f32_e32 v182, v182, v85
	v_add_f32_e32 v182, v182, v86
	v_add_f32_e32 v182, v182, v87
	v_mfma_f32_32x32x16_bf16 v[16:31], v[198:201], v[210:213], v[16:31]
	v_add_f32_e32 v182, v182, v88
	v_add_f32_e32 v182, v182, v89
	v_add_f32_e32 v182, v182, v90
	v_add_f32_e32 v182, v182, v91
	v_mfma_f32_32x32x16_bf16 v[0:15], v[198:201], v[214:217], v[0:15]
	v_add_f32_e32 v182, v182, v92
	v_add_f32_e32 v182, v182, v93
	v_add_f32_e32 v182, v182, v94
	v_add_f32_e32 v182, v182, v95
